# GEMM K-loops: loop-carried counter / pointer updates and exit test moved in front of the loop-back barrier (back-edge rotation)
# baseline (speedup 1.0000x reference)
.LBB0_398:
	ds_read_b128 v[146:149], v164
	ds_read_b128 v[150:153], v164 offset:1024
	ds_read_b128 v[154:157], v164 offset:2048
	ds_read_b128 v[168:171], v164 offset:3072
	ds_read_b128 v[172:175], v165
	ds_read_b128 v[176:179], v165 offset:1024
	ds_read_b128 v[180:183], v165 offset:2048
	ds_read_b128 v[184:187], v165 offset:3072
	s_add_u32 s48, s46, 0xfffc0080
	s_addc_u32 s49, s47, -1
	s_cmp_eq_u32 s87, 12
	s_cselect_b32 s55, s31, s49
	s_cselect_b32 s54, s45, s48
	s_cselect_b32 s49, s29, s86
	s_cselect_b32 s48, s78, s85
	v_lshl_add_u64 v[158:159], s[46:47], 0, v[138:139]
	s_add_i32 m0, s66, 0xc000
	ds_read_b128 v[188:191], v166
	ds_read_b128 v[192:195], v166 offset:1024
	ds_read_b128 v[196:199], v166 offset:2048
	ds_read_b128 v[200:203], v166 offset:3072
	ds_read_b128 v[208:211], v166 offset:4096
	ds_read_b128 v[212:215], v166 offset:5120
	ds_read_b128 v[216:219], v166 offset:6144
	ds_read_b128 v[220:223], v166 offset:7168
	global_load_lds_dwordx4 v[158:159], off
	v_lshl_add_u64 v[158:159], s[46:47], 0, v[140:141]
	s_add_i32 m0, s66, 0xe000
	s_nop 0
	global_load_lds_dwordx4 v[158:159], off
	s_waitcnt vmcnt(8)
	s_waitcnt lgkmcnt(0)
	s_barrier
	s_setprio 1
	s_waitcnt lgkmcnt(0)
	v_mfma_f32_16x16x32_bf16 v[84:87], v[146:149], v[188:191], v[84:87]
	v_mfma_f32_16x16x32_bf16 v[80:83], v[154:157], v[188:191], v[80:83]
	v_mfma_f32_16x16x32_bf16 v[76:79], v[146:149], v[196:199], v[76:79]
	v_mfma_f32_16x16x32_bf16 v[72:75], v[154:157], v[196:199], v[72:75]
	v_mfma_f32_16x16x32_bf16 v[68:71], v[146:149], v[208:211], v[68:71]
	v_mfma_f32_16x16x32_bf16 v[64:67], v[154:157], v[208:211], v[64:67]
	v_mfma_f32_16x16x32_bf16 v[60:63], v[146:149], v[216:219], v[60:63]
	v_mfma_f32_16x16x32_bf16 v[56:59], v[154:157], v[216:219], v[56:59]
	v_mfma_f32_16x16x32_bf16 v[84:87], v[150:153], v[192:195], v[84:87]
	v_mfma_f32_16x16x32_bf16 v[80:83], v[168:171], v[192:195], v[80:83]
	v_mfma_f32_16x16x32_bf16 v[76:79], v[150:153], v[200:203], v[76:79]
	v_mfma_f32_16x16x32_bf16 v[72:75], v[168:171], v[200:203], v[72:75]
	v_mfma_f32_16x16x32_bf16 v[68:71], v[150:153], v[212:215], v[68:71]
	v_mfma_f32_16x16x32_bf16 v[64:67], v[168:171], v[212:215], v[64:67]
	v_mfma_f32_16x16x32_bf16 v[60:63], v[150:153], v[220:223], v[60:63]
	v_mfma_f32_16x16x32_bf16 v[56:59], v[168:171], v[220:223], v[56:59]
	s_setprio 0
	s_setprio 1
	v_mfma_f32_16x16x32_bf16 v[124:127], v[172:175], v[188:191], v[124:127]
	v_mfma_f32_16x16x32_bf16 v[120:123], v[180:183], v[188:191], v[120:123]
	v_mfma_f32_16x16x32_bf16 v[116:119], v[172:175], v[196:199], v[116:119]
	v_mfma_f32_16x16x32_bf16 v[112:115], v[180:183], v[196:199], v[112:115]
	v_mfma_f32_16x16x32_bf16 v[108:111], v[172:175], v[208:211], v[108:111]
	v_mfma_f32_16x16x32_bf16 v[104:107], v[180:183], v[208:211], v[104:107]
	v_mfma_f32_16x16x32_bf16 v[100:103], v[172:175], v[216:219], v[100:103]
	v_mfma_f32_16x16x32_bf16 v[96:99], v[180:183], v[216:219], v[96:99]
	v_mfma_f32_16x16x32_bf16 v[124:127], v[176:179], v[192:195], v[124:127]
	v_mfma_f32_16x16x32_bf16 v[120:123], v[184:187], v[192:195], v[120:123]
	v_mfma_f32_16x16x32_bf16 v[116:119], v[176:179], v[200:203], v[116:119]
	v_mfma_f32_16x16x32_bf16 v[112:115], v[184:187], v[200:203], v[112:115]
	v_mfma_f32_16x16x32_bf16 v[108:111], v[176:179], v[212:215], v[108:111]
	v_mfma_f32_16x16x32_bf16 v[104:107], v[184:187], v[212:215], v[104:107]
	v_mfma_f32_16x16x32_bf16 v[100:103], v[176:179], v[220:223], v[100:103]
	v_mfma_f32_16x16x32_bf16 v[96:99], v[184:187], v[220:223], v[96:99]
	s_setprio 0
	s_barrier
	s_add_i32 s88, s76, s38
	v_lshl_add_u64 v[158:159], s[48:49], 0, v[132:133]
	s_mov_b32 m0, s88
	ds_read_b128 v[188:191], v166 offset:16384
	ds_read_b128 v[192:195], v166 offset:17408
	ds_read_b128 v[196:199], v166 offset:18432
	ds_read_b128 v[200:203], v166 offset:19456
	ds_read_b128 v[208:211], v166 offset:20480
	ds_read_b128 v[212:215], v166 offset:21504
	ds_read_b128 v[216:219], v166 offset:22528
	ds_read_b128 v[220:223], v166 offset:23552
	global_load_lds_dwordx4 v[158:159], off
	s_add_i32 m0, s88, 0x2000
	s_add_u32 s88, s48, 0x40000
	v_lshl_add_u64 v[204:205], s[48:49], 0, v[128:129]
	s_addc_u32 s89, s49, 0
	s_add_i32 s90, s77, s38
	global_load_lds_dwordx4 v[204:205], off
	v_lshl_add_u64 v[224:225], s[88:89], 0, v[132:133]
	s_mov_b32 m0, s90
	v_lshl_add_u64 v[226:227], s[54:55], 0, v[130:131]
	global_load_lds_dwordx4 v[224:225], off
	v_lshl_add_u64 v[224:225], s[88:89], 0, v[128:129]
	s_add_i32 m0, s90, 0x2000
	s_nop 0
	global_load_lds_dwordx4 v[224:225], off
	v_lshl_add_u64 v[224:225], s[54:55], 0, v[134:135]
	s_mov_b32 m0, s66
	s_nop 0
	global_load_lds_dwordx4 v[224:225], off
	s_mov_b32 m0, s67
	s_nop 0
	global_load_lds_dwordx4 v[226:227], off
	s_waitcnt vmcnt(8)
	s_waitcnt lgkmcnt(0)
	s_barrier
	s_setprio 1
	s_waitcnt lgkmcnt(0)
	v_mfma_f32_16x16x32_bf16 v[52:55], v[146:149], v[188:191], v[52:55]
	v_mfma_f32_16x16x32_bf16 v[48:51], v[154:157], v[188:191], v[48:51]
	v_mfma_f32_16x16x32_bf16 v[44:47], v[146:149], v[196:199], v[44:47]
	v_mfma_f32_16x16x32_bf16 v[40:43], v[154:157], v[196:199], v[40:43]
	v_mfma_f32_16x16x32_bf16 v[28:31], v[146:149], v[208:211], v[28:31]
	v_mfma_f32_16x16x32_bf16 v[24:27], v[154:157], v[208:211], v[24:27]
	v_mfma_f32_16x16x32_bf16 v[12:15], v[146:149], v[216:219], v[12:15]
	v_mfma_f32_16x16x32_bf16 v[8:11], v[154:157], v[216:219], v[8:11]
	v_mfma_f32_16x16x32_bf16 v[52:55], v[150:153], v[192:195], v[52:55]
	v_mfma_f32_16x16x32_bf16 v[48:51], v[168:171], v[192:195], v[48:51]
	v_mfma_f32_16x16x32_bf16 v[44:47], v[150:153], v[200:203], v[44:47]
	v_mfma_f32_16x16x32_bf16 v[40:43], v[168:171], v[200:203], v[40:43]
	v_mfma_f32_16x16x32_bf16 v[28:31], v[150:153], v[212:215], v[28:31]
	v_mfma_f32_16x16x32_bf16 v[24:27], v[168:171], v[212:215], v[24:27]
	v_mfma_f32_16x16x32_bf16 v[12:15], v[150:153], v[220:223], v[12:15]
	v_mfma_f32_16x16x32_bf16 v[8:11], v[168:171], v[220:223], v[8:11]
	s_setprio 0
	s_setprio 1
	v_mfma_f32_16x16x32_bf16 v[92:95], v[172:175], v[188:191], v[92:95]
	v_mfma_f32_16x16x32_bf16 v[88:91], v[180:183], v[188:191], v[88:91]
	v_mfma_f32_16x16x32_bf16 v[36:39], v[172:175], v[196:199], v[36:39]
	v_mfma_f32_16x16x32_bf16 v[32:35], v[180:183], v[196:199], v[32:35]
	v_mfma_f32_16x16x32_bf16 v[20:23], v[172:175], v[208:211], v[20:23]
	v_mfma_f32_16x16x32_bf16 v[16:19], v[180:183], v[208:211], v[16:19]
	v_mfma_f32_16x16x32_bf16 v[4:7], v[172:175], v[216:219], v[4:7]
	v_mfma_f32_16x16x32_bf16 v[0:3], v[180:183], v[216:219], v[0:3]
	v_mfma_f32_16x16x32_bf16 v[92:95], v[176:179], v[192:195], v[92:95]
	v_mfma_f32_16x16x32_bf16 v[88:91], v[184:187], v[192:195], v[88:91]
	v_mfma_f32_16x16x32_bf16 v[36:39], v[176:179], v[200:203], v[36:39]
	v_mfma_f32_16x16x32_bf16 v[32:35], v[184:187], v[200:203], v[32:35]
	v_mfma_f32_16x16x32_bf16 v[20:23], v[176:179], v[212:215], v[20:23]
	v_mfma_f32_16x16x32_bf16 v[16:19], v[184:187], v[212:215], v[16:19]
	v_mfma_f32_16x16x32_bf16 v[4:7], v[176:179], v[220:223], v[4:7]
	v_mfma_f32_16x16x32_bf16 v[0:3], v[184:187], v[220:223], v[0:3]
	s_setprio 0
	s_barrier
	s_add_i32 s88, 0, 0x18000
	v_add_u32_e32 v136, s88, v161
	s_add_i32 s89, 0, 0x1c000
	ds_read_b128 v[146:149], v136
	ds_read_b128 v[150:153], v136 offset:1024
	ds_read_b128 v[154:157], v136 offset:2048
	ds_read_b128 v[168:171], v136 offset:3072
	v_add_u32_e32 v136, s89, v161
	ds_read_b128 v[172:175], v136
	ds_read_b128 v[176:179], v136 offset:1024
	ds_read_b128 v[180:183], v136 offset:2048
	ds_read_b128 v[184:187], v136 offset:3072
	s_add_u32 s54, s54, 0x40000
	s_addc_u32 s55, s55, 0
	s_mov_b32 m0, s70
	v_lshl_add_u64 v[228:229], s[54:55], 0, v[134:135]
	ds_read_b128 v[188:191], v166 offset:32768
	ds_read_b128 v[192:195], v166 offset:33792
	ds_read_b128 v[196:199], v166 offset:34816
	ds_read_b128 v[200:203], v166 offset:35840
	ds_read_b128 v[208:211], v166 offset:36864
	ds_read_b128 v[212:215], v166 offset:37888
	ds_read_b128 v[216:219], v166 offset:38912
	ds_read_b128 v[220:223], v166 offset:39936
	global_load_lds_dwordx4 v[228:229], off
	v_lshl_add_u64 v[228:229], s[54:55], 0, v[130:131]
	s_mov_b32 m0, s71
	s_nop 0
	global_load_lds_dwordx4 v[228:229], off
	s_waitcnt vmcnt(8)
	s_waitcnt lgkmcnt(0)
	s_barrier
	s_setprio 1
	s_waitcnt lgkmcnt(0)
	v_mfma_f32_16x16x32_bf16 v[84:87], v[146:149], v[188:191], v[84:87]
	v_mfma_f32_16x16x32_bf16 v[80:83], v[154:157], v[188:191], v[80:83]
	v_mfma_f32_16x16x32_bf16 v[76:79], v[146:149], v[196:199], v[76:79]
	v_mfma_f32_16x16x32_bf16 v[72:75], v[154:157], v[196:199], v[72:75]
	v_mfma_f32_16x16x32_bf16 v[68:71], v[146:149], v[208:211], v[68:71]
	v_mfma_f32_16x16x32_bf16 v[64:67], v[154:157], v[208:211], v[64:67]
	v_mfma_f32_16x16x32_bf16 v[60:63], v[146:149], v[216:219], v[60:63]
	v_mfma_f32_16x16x32_bf16 v[56:59], v[154:157], v[216:219], v[56:59]
	v_mfma_f32_16x16x32_bf16 v[84:87], v[150:153], v[192:195], v[84:87]
	v_mfma_f32_16x16x32_bf16 v[80:83], v[168:171], v[192:195], v[80:83]
	v_mfma_f32_16x16x32_bf16 v[76:79], v[150:153], v[200:203], v[76:79]
	v_mfma_f32_16x16x32_bf16 v[72:75], v[168:171], v[200:203], v[72:75]
	v_mfma_f32_16x16x32_bf16 v[68:71], v[150:153], v[212:215], v[68:71]
	v_mfma_f32_16x16x32_bf16 v[64:67], v[168:171], v[212:215], v[64:67]
	v_mfma_f32_16x16x32_bf16 v[60:63], v[150:153], v[220:223], v[60:63]
	v_mfma_f32_16x16x32_bf16 v[56:59], v[168:171], v[220:223], v[56:59]
	s_setprio 0
	s_setprio 1
	v_mfma_f32_16x16x32_bf16 v[124:127], v[172:175], v[188:191], v[124:127]
	v_mfma_f32_16x16x32_bf16 v[120:123], v[180:183], v[188:191], v[120:123]
	v_mfma_f32_16x16x32_bf16 v[116:119], v[172:175], v[196:199], v[116:119]
	v_mfma_f32_16x16x32_bf16 v[112:115], v[180:183], v[196:199], v[112:115]
	v_mfma_f32_16x16x32_bf16 v[108:111], v[172:175], v[208:211], v[108:111]
	v_mfma_f32_16x16x32_bf16 v[104:107], v[180:183], v[208:211], v[104:107]
	v_mfma_f32_16x16x32_bf16 v[100:103], v[172:175], v[216:219], v[100:103]
	v_mfma_f32_16x16x32_bf16 v[96:99], v[180:183], v[216:219], v[96:99]
	v_mfma_f32_16x16x32_bf16 v[124:127], v[176:179], v[192:195], v[124:127]
	v_mfma_f32_16x16x32_bf16 v[120:123], v[184:187], v[192:195], v[120:123]
	v_mfma_f32_16x16x32_bf16 v[116:119], v[176:179], v[200:203], v[116:119]
	v_mfma_f32_16x16x32_bf16 v[112:115], v[184:187], v[200:203], v[112:115]
	v_mfma_f32_16x16x32_bf16 v[108:111], v[176:179], v[212:215], v[108:111]
	v_mfma_f32_16x16x32_bf16 v[104:107], v[184:187], v[212:215], v[104:107]
	v_mfma_f32_16x16x32_bf16 v[100:103], v[176:179], v[220:223], v[100:103]
	v_mfma_f32_16x16x32_bf16 v[96:99], v[184:187], v[220:223], v[96:99]
	s_setprio 0
	s_barrier
	s_add_i32 s54, s88, s38
	v_lshl_add_u64 v[158:159], v[158:159], 0, s[10:11]
	s_mov_b32 m0, s54
	ds_read_b128 v[188:191], v166 offset:49152
	ds_read_b128 v[192:195], v166 offset:50176
	ds_read_b128 v[196:199], v166 offset:51200
	ds_read_b128 v[200:203], v166 offset:52224
	ds_read_b128 v[208:211], v166 offset:53248
	ds_read_b128 v[212:215], v166 offset:54272
	ds_read_b128 v[216:219], v166 offset:55296
	ds_read_b128 v[220:223], v166 offset:56320
	global_load_lds_dwordx4 v[158:159], off
	s_add_i32 m0, s54, 0x2000
	s_add_u32 s48, s48, 0x40080
	v_lshl_add_u64 v[158:159], v[204:205], 0, s[10:11]
	s_addc_u32 s49, s49, 0
	s_add_i32 s54, s89, s38
	global_load_lds_dwordx4 v[158:159], off
	v_lshl_add_u64 v[158:159], s[48:49], 0, v[132:133]
	s_mov_b32 m0, s54
	s_nop 0
	global_load_lds_dwordx4 v[158:159], off
	v_lshl_add_u64 v[158:159], s[48:49], 0, v[128:129]
	s_add_i32 m0, s54, 0x2000
	s_nop 0
	global_load_lds_dwordx4 v[158:159], off
	v_lshl_add_u64 v[158:159], v[224:225], 0, s[10:11]
	s_mov_b32 m0, s73
	s_nop 0
	global_load_lds_dwordx4 v[158:159], off
	v_lshl_add_u64 v[158:159], v[226:227], 0, s[10:11]
	s_mov_b32 m0, s74
	s_nop 0
	global_load_lds_dwordx4 v[158:159], off
	s_waitcnt vmcnt(8)
	s_waitcnt lgkmcnt(0)
	s_barrier
	s_setprio 1
	s_waitcnt lgkmcnt(0)
	v_mfma_f32_16x16x32_bf16 v[52:55], v[146:149], v[188:191], v[52:55]
	v_mfma_f32_16x16x32_bf16 v[48:51], v[154:157], v[188:191], v[48:51]
	v_mfma_f32_16x16x32_bf16 v[44:47], v[146:149], v[196:199], v[44:47]
	v_mfma_f32_16x16x32_bf16 v[40:43], v[154:157], v[196:199], v[40:43]
	v_mfma_f32_16x16x32_bf16 v[28:31], v[146:149], v[208:211], v[28:31]
	v_mfma_f32_16x16x32_bf16 v[24:27], v[154:157], v[208:211], v[24:27]
	v_mfma_f32_16x16x32_bf16 v[12:15], v[146:149], v[216:219], v[12:15]
	v_mfma_f32_16x16x32_bf16 v[8:11], v[154:157], v[216:219], v[8:11]
	v_mfma_f32_16x16x32_bf16 v[52:55], v[150:153], v[192:195], v[52:55]
	v_mfma_f32_16x16x32_bf16 v[48:51], v[168:171], v[192:195], v[48:51]
	v_mfma_f32_16x16x32_bf16 v[44:47], v[150:153], v[200:203], v[44:47]
	v_mfma_f32_16x16x32_bf16 v[40:43], v[168:171], v[200:203], v[40:43]
	v_mfma_f32_16x16x32_bf16 v[28:31], v[150:153], v[212:215], v[28:31]
	v_mfma_f32_16x16x32_bf16 v[24:27], v[168:171], v[212:215], v[24:27]
	v_mfma_f32_16x16x32_bf16 v[12:15], v[150:153], v[220:223], v[12:15]
	v_mfma_f32_16x16x32_bf16 v[8:11], v[168:171], v[220:223], v[8:11]
	s_setprio 0
	s_setprio 1
	v_mfma_f32_16x16x32_bf16 v[92:95], v[172:175], v[188:191], v[92:95]
	v_mfma_f32_16x16x32_bf16 v[88:91], v[180:183], v[188:191], v[88:91]
	v_mfma_f32_16x16x32_bf16 v[36:39], v[172:175], v[196:199], v[36:39]
	v_mfma_f32_16x16x32_bf16 v[32:35], v[180:183], v[196:199], v[32:35]
	v_mfma_f32_16x16x32_bf16 v[20:23], v[172:175], v[208:211], v[20:23]
	v_mfma_f32_16x16x32_bf16 v[16:19], v[180:183], v[208:211], v[16:19]
	v_mfma_f32_16x16x32_bf16 v[4:7], v[172:175], v[216:219], v[4:7]
	v_mfma_f32_16x16x32_bf16 v[0:3], v[180:183], v[216:219], v[0:3]
	v_mfma_f32_16x16x32_bf16 v[92:95], v[176:179], v[192:195], v[92:95]
	v_mfma_f32_16x16x32_bf16 v[88:91], v[184:187], v[192:195], v[88:91]
	v_mfma_f32_16x16x32_bf16 v[36:39], v[176:179], v[200:203], v[36:39]
	v_mfma_f32_16x16x32_bf16 v[32:35], v[184:187], v[200:203], v[32:35]
	v_mfma_f32_16x16x32_bf16 v[20:23], v[176:179], v[212:215], v[20:23]
	v_mfma_f32_16x16x32_bf16 v[16:19], v[184:187], v[212:215], v[16:19]
	v_mfma_f32_16x16x32_bf16 v[4:7], v[176:179], v[220:223], v[4:7]
	v_mfma_f32_16x16x32_bf16 v[0:3], v[184:187], v[220:223], v[0:3]
	s_setprio 0
	s_add_i32 s87, s87, 2
	s_add_u32 s46, s46, 0x100
	s_addc_u32 s47, s47, 0
	s_add_u32 s85, s85, 0x100
	s_addc_u32 s86, s86, 0
	s_cmp_gt_u32 s87, 13
	s_barrier
	s_cbranch_scc0 .LBB0_398
	s_and_b64 vcc, exec, s[12:13]
	s_cbranch_vccz .LBB0_401
	s_barrier

.LBB0_525:
	ds_read_b128 v[150:153], v147
	ds_read_b128 v[154:157], v147 offset:1024
	ds_read_b128 v[158:161], v147 offset:2048
	ds_read_b128 v[162:165], v147 offset:3072
	ds_read_b128 v[166:169], v148
	ds_read_b128 v[170:173], v148 offset:1024
	ds_read_b128 v[174:177], v148 offset:2048
	ds_read_b128 v[178:181], v148 offset:3072
	s_add_u32 s34, s30, 0xfffc0080
	s_addc_u32 s35, s31, -1
	s_cmp_eq_u32 s82, 12
	s_cselect_b32 s37, s25, s35
	s_cselect_b32 s36, s77, s34
	s_cselect_b32 s35, s23, s81
	s_cselect_b32 s34, s78, s79
	v_lshl_add_u64 v[216:217], s[30:31], 0, v[136:137]
	s_add_i32 m0, s21, 0xc000
	ds_read_b128 v[182:185], v149
	ds_read_b128 v[186:189], v149 offset:1024
	ds_read_b128 v[190:193], v149 offset:2048
	ds_read_b128 v[194:197], v149 offset:3072
	ds_read_b128 v[198:201], v149 offset:4096
	ds_read_b128 v[202:205], v149 offset:5120
	ds_read_b128 v[208:211], v149 offset:6144
	ds_read_b128 v[212:215], v149 offset:7168
	global_load_lds_dwordx4 v[216:217], off
	v_lshl_add_u64 v[216:217], s[30:31], 0, v[138:139]
	s_add_i32 m0, s21, 0xe000
	s_nop 0
	global_load_lds_dwordx4 v[216:217], off
	s_waitcnt vmcnt(8)
	s_waitcnt lgkmcnt(0)
	s_barrier
	s_setprio 1
	s_waitcnt lgkmcnt(0)
	v_mfma_f32_16x16x32_bf16 v[124:127], v[150:153], v[182:185], v[124:127]
	v_mfma_f32_16x16x32_bf16 v[120:123], v[158:161], v[182:185], v[120:123]
	v_mfma_f32_16x16x32_bf16 v[116:119], v[150:153], v[190:193], v[116:119]
	v_mfma_f32_16x16x32_bf16 v[112:115], v[158:161], v[190:193], v[112:115]
	v_mfma_f32_16x16x32_bf16 v[100:103], v[150:153], v[198:201], v[100:103]
	v_mfma_f32_16x16x32_bf16 v[96:99], v[158:161], v[198:201], v[96:99]
	v_mfma_f32_16x16x32_bf16 v[84:87], v[150:153], v[208:211], v[84:87]
	v_mfma_f32_16x16x32_bf16 v[80:83], v[158:161], v[208:211], v[80:83]
	v_mfma_f32_16x16x32_bf16 v[124:127], v[154:157], v[186:189], v[124:127]
	v_mfma_f32_16x16x32_bf16 v[120:123], v[162:165], v[186:189], v[120:123]
	v_mfma_f32_16x16x32_bf16 v[116:119], v[154:157], v[194:197], v[116:119]
	v_mfma_f32_16x16x32_bf16 v[112:115], v[162:165], v[194:197], v[112:115]
	v_mfma_f32_16x16x32_bf16 v[100:103], v[154:157], v[202:205], v[100:103]
	v_mfma_f32_16x16x32_bf16 v[96:99], v[162:165], v[202:205], v[96:99]
	v_mfma_f32_16x16x32_bf16 v[84:87], v[154:157], v[212:215], v[84:87]
	v_mfma_f32_16x16x32_bf16 v[80:83], v[162:165], v[212:215], v[80:83]
	s_setprio 0
	s_setprio 1
	v_mfma_f32_16x16x32_bf16 v[108:111], v[166:169], v[182:185], v[108:111]
	v_mfma_f32_16x16x32_bf16 v[104:107], v[174:177], v[182:185], v[104:107]
	v_mfma_f32_16x16x32_bf16 v[92:95], v[166:169], v[190:193], v[92:95]
	v_mfma_f32_16x16x32_bf16 v[88:91], v[174:177], v[190:193], v[88:91]
	v_mfma_f32_16x16x32_bf16 v[76:79], v[166:169], v[198:201], v[76:79]
	v_mfma_f32_16x16x32_bf16 v[72:75], v[174:177], v[198:201], v[72:75]
	v_mfma_f32_16x16x32_bf16 v[68:71], v[166:169], v[208:211], v[68:71]
	v_mfma_f32_16x16x32_bf16 v[64:67], v[174:177], v[208:211], v[64:67]
	v_mfma_f32_16x16x32_bf16 v[108:111], v[170:173], v[186:189], v[108:111]
	v_mfma_f32_16x16x32_bf16 v[104:107], v[178:181], v[186:189], v[104:107]
	v_mfma_f32_16x16x32_bf16 v[92:95], v[170:173], v[194:197], v[92:95]
	v_mfma_f32_16x16x32_bf16 v[88:91], v[178:181], v[194:197], v[88:91]
	v_mfma_f32_16x16x32_bf16 v[76:79], v[170:173], v[202:205], v[76:79]
	v_mfma_f32_16x16x32_bf16 v[72:75], v[178:181], v[202:205], v[72:75]
	v_mfma_f32_16x16x32_bf16 v[68:71], v[170:173], v[212:215], v[68:71]
	v_mfma_f32_16x16x32_bf16 v[64:67], v[178:181], v[212:215], v[64:67]
	s_setprio 0
	s_barrier
	s_add_i32 s83, s70, s47
	v_lshl_add_u64 v[216:217], s[34:35], 0, v[130:131]
	s_mov_b32 m0, s83
	ds_read_b128 v[182:185], v149 offset:16384
	ds_read_b128 v[186:189], v149 offset:17408
	ds_read_b128 v[190:193], v149 offset:18432
	ds_read_b128 v[194:197], v149 offset:19456
	ds_read_b128 v[198:201], v149 offset:20480
	ds_read_b128 v[202:205], v149 offset:21504
	ds_read_b128 v[208:211], v149 offset:22528
	ds_read_b128 v[212:215], v149 offset:23552
	global_load_lds_dwordx4 v[216:217], off
	s_add_i32 m0, s83, 0x2000
	s_add_u32 s84, s34, 0x40000
	v_lshl_add_u64 v[218:219], s[34:35], 0, v[134:135]
	s_addc_u32 s85, s35, 0
	s_add_i32 s83, s71, s47
	global_load_lds_dwordx4 v[218:219], off
	v_lshl_add_u64 v[220:221], s[84:85], 0, v[130:131]
	s_mov_b32 m0, s83
	v_lshl_add_u64 v[222:223], s[36:37], 0, v[132:133]
	global_load_lds_dwordx4 v[220:221], off
	v_lshl_add_u64 v[220:221], s[84:85], 0, v[134:135]
	s_add_i32 m0, s83, 0x2000
	s_nop 0
	global_load_lds_dwordx4 v[220:221], off
	v_lshl_add_u64 v[220:221], s[36:37], 0, v[128:129]
	s_mov_b32 m0, s21
	s_nop 0
	global_load_lds_dwordx4 v[220:221], off
	s_mov_b32 m0, s48
	s_nop 0
	global_load_lds_dwordx4 v[222:223], off
	s_waitcnt vmcnt(8)
	s_waitcnt lgkmcnt(0)
	s_barrier
	s_setprio 1
	s_waitcnt lgkmcnt(0)
	v_mfma_f32_16x16x32_bf16 v[60:63], v[150:153], v[182:185], v[60:63]
	v_mfma_f32_16x16x32_bf16 v[56:59], v[158:161], v[182:185], v[56:59]
	v_mfma_f32_16x16x32_bf16 v[52:55], v[150:153], v[190:193], v[52:55]
	v_mfma_f32_16x16x32_bf16 v[48:51], v[158:161], v[190:193], v[48:51]
	v_mfma_f32_16x16x32_bf16 v[36:39], v[150:153], v[198:201], v[36:39]
	v_mfma_f32_16x16x32_bf16 v[32:35], v[158:161], v[198:201], v[32:35]
	v_mfma_f32_16x16x32_bf16 v[20:23], v[150:153], v[208:211], v[20:23]
	v_mfma_f32_16x16x32_bf16 v[16:19], v[158:161], v[208:211], v[16:19]
	v_mfma_f32_16x16x32_bf16 v[60:63], v[154:157], v[186:189], v[60:63]
	v_mfma_f32_16x16x32_bf16 v[56:59], v[162:165], v[186:189], v[56:59]
	v_mfma_f32_16x16x32_bf16 v[52:55], v[154:157], v[194:197], v[52:55]
	v_mfma_f32_16x16x32_bf16 v[48:51], v[162:165], v[194:197], v[48:51]
	v_mfma_f32_16x16x32_bf16 v[36:39], v[154:157], v[202:205], v[36:39]
	v_mfma_f32_16x16x32_bf16 v[32:35], v[162:165], v[202:205], v[32:35]
	v_mfma_f32_16x16x32_bf16 v[20:23], v[154:157], v[212:215], v[20:23]
	v_mfma_f32_16x16x32_bf16 v[16:19], v[162:165], v[212:215], v[16:19]
	s_setprio 0
	s_setprio 1
	v_mfma_f32_16x16x32_bf16 v[44:47], v[166:169], v[182:185], v[44:47]
	v_mfma_f32_16x16x32_bf16 v[40:43], v[174:177], v[182:185], v[40:43]
	v_mfma_f32_16x16x32_bf16 v[28:31], v[166:169], v[190:193], v[28:31]
	v_mfma_f32_16x16x32_bf16 v[24:27], v[174:177], v[190:193], v[24:27]
	v_mfma_f32_16x16x32_bf16 v[12:15], v[166:169], v[198:201], v[12:15]
	v_mfma_f32_16x16x32_bf16 v[8:11], v[174:177], v[198:201], v[8:11]
	v_mfma_f32_16x16x32_bf16 v[4:7], v[166:169], v[208:211], v[4:7]
	v_mfma_f32_16x16x32_bf16 v[0:3], v[174:177], v[208:211], v[0:3]
	v_mfma_f32_16x16x32_bf16 v[44:47], v[170:173], v[186:189], v[44:47]
	v_mfma_f32_16x16x32_bf16 v[40:43], v[178:181], v[186:189], v[40:43]
	v_mfma_f32_16x16x32_bf16 v[28:31], v[170:173], v[194:197], v[28:31]
	v_mfma_f32_16x16x32_bf16 v[24:27], v[178:181], v[194:197], v[24:27]
	v_mfma_f32_16x16x32_bf16 v[12:15], v[170:173], v[202:205], v[12:15]
	v_mfma_f32_16x16x32_bf16 v[8:11], v[178:181], v[202:205], v[8:11]
	v_mfma_f32_16x16x32_bf16 v[4:7], v[170:173], v[212:215], v[4:7]
	v_mfma_f32_16x16x32_bf16 v[0:3], v[178:181], v[212:215], v[0:3]
	s_setprio 0
	s_barrier
	s_add_i32 s83, 0, 0x18000
	s_add_i32 s84, 0, 0x1c000
	v_add_u32_e32 v162, s83, v145
	v_add_u32_e32 v178, s84, v145
	ds_read_b128 v[150:153], v162
	ds_read_b128 v[154:157], v162 offset:1024
	ds_read_b128 v[158:161], v162 offset:2048
	ds_read_b128 v[162:165], v162 offset:3072
	ds_read_b128 v[166:169], v178
	ds_read_b128 v[170:173], v178 offset:1024
	ds_read_b128 v[174:177], v178 offset:2048
	ds_read_b128 v[178:181], v178 offset:3072
	s_add_u32 s36, s36, 0x40000
	s_addc_u32 s37, s37, 0
	s_mov_b32 m0, s49
	v_lshl_add_u64 v[224:225], s[36:37], 0, v[128:129]
	ds_read_b128 v[182:185], v149 offset:32768
	ds_read_b128 v[186:189], v149 offset:33792
	ds_read_b128 v[190:193], v149 offset:34816
	ds_read_b128 v[194:197], v149 offset:35840
	ds_read_b128 v[198:201], v149 offset:36864
	ds_read_b128 v[202:205], v149 offset:37888
	ds_read_b128 v[208:211], v149 offset:38912
	ds_read_b128 v[212:215], v149 offset:39936
	global_load_lds_dwordx4 v[224:225], off
	v_lshl_add_u64 v[224:225], s[36:37], 0, v[132:133]
	s_mov_b32 m0, s54
	s_nop 0
	global_load_lds_dwordx4 v[224:225], off
	s_waitcnt vmcnt(8)
	s_waitcnt lgkmcnt(0)
	s_barrier
	s_setprio 1
	s_waitcnt lgkmcnt(0)
	v_mfma_f32_16x16x32_bf16 v[124:127], v[150:153], v[182:185], v[124:127]
	v_mfma_f32_16x16x32_bf16 v[120:123], v[158:161], v[182:185], v[120:123]
	v_mfma_f32_16x16x32_bf16 v[116:119], v[150:153], v[190:193], v[116:119]
	v_mfma_f32_16x16x32_bf16 v[112:115], v[158:161], v[190:193], v[112:115]
	v_mfma_f32_16x16x32_bf16 v[100:103], v[150:153], v[198:201], v[100:103]
	v_mfma_f32_16x16x32_bf16 v[96:99], v[158:161], v[198:201], v[96:99]
	v_mfma_f32_16x16x32_bf16 v[84:87], v[150:153], v[208:211], v[84:87]
	v_mfma_f32_16x16x32_bf16 v[80:83], v[158:161], v[208:211], v[80:83]
	v_mfma_f32_16x16x32_bf16 v[124:127], v[154:157], v[186:189], v[124:127]
	v_mfma_f32_16x16x32_bf16 v[120:123], v[162:165], v[186:189], v[120:123]
	v_mfma_f32_16x16x32_bf16 v[116:119], v[154:157], v[194:197], v[116:119]
	v_mfma_f32_16x16x32_bf16 v[112:115], v[162:165], v[194:197], v[112:115]
	v_mfma_f32_16x16x32_bf16 v[100:103], v[154:157], v[202:205], v[100:103]
	v_mfma_f32_16x16x32_bf16 v[96:99], v[162:165], v[202:205], v[96:99]
	v_mfma_f32_16x16x32_bf16 v[84:87], v[154:157], v[212:215], v[84:87]
	v_mfma_f32_16x16x32_bf16 v[80:83], v[162:165], v[212:215], v[80:83]
	s_setprio 0
	s_setprio 1
	v_mfma_f32_16x16x32_bf16 v[108:111], v[166:169], v[182:185], v[108:111]
	v_mfma_f32_16x16x32_bf16 v[104:107], v[174:177], v[182:185], v[104:107]
	v_mfma_f32_16x16x32_bf16 v[92:95], v[166:169], v[190:193], v[92:95]
	v_mfma_f32_16x16x32_bf16 v[88:91], v[174:177], v[190:193], v[88:91]
	v_mfma_f32_16x16x32_bf16 v[76:79], v[166:169], v[198:201], v[76:79]
	v_mfma_f32_16x16x32_bf16 v[72:75], v[174:177], v[198:201], v[72:75]
	v_mfma_f32_16x16x32_bf16 v[68:71], v[166:169], v[208:211], v[68:71]
	v_mfma_f32_16x16x32_bf16 v[64:67], v[174:177], v[208:211], v[64:67]
	v_mfma_f32_16x16x32_bf16 v[108:111], v[170:173], v[186:189], v[108:111]
	v_mfma_f32_16x16x32_bf16 v[104:107], v[178:181], v[186:189], v[104:107]
	v_mfma_f32_16x16x32_bf16 v[92:95], v[170:173], v[194:197], v[92:95]
	v_mfma_f32_16x16x32_bf16 v[88:91], v[178:181], v[194:197], v[88:91]
	v_mfma_f32_16x16x32_bf16 v[76:79], v[170:173], v[202:205], v[76:79]
	v_mfma_f32_16x16x32_bf16 v[72:75], v[178:181], v[202:205], v[72:75]
	v_mfma_f32_16x16x32_bf16 v[68:71], v[170:173], v[212:215], v[68:71]
	v_mfma_f32_16x16x32_bf16 v[64:67], v[178:181], v[212:215], v[64:67]
	s_setprio 0
	s_barrier
	s_add_i32 s36, s83, s47
	v_lshl_add_u64 v[216:217], v[216:217], 0, s[10:11]
	s_mov_b32 m0, s36
	ds_read_b128 v[182:185], v149 offset:49152
	ds_read_b128 v[186:189], v149 offset:50176
	ds_read_b128 v[190:193], v149 offset:51200
	ds_read_b128 v[194:197], v149 offset:52224
	ds_read_b128 v[198:201], v149 offset:53248
	ds_read_b128 v[202:205], v149 offset:54272
	ds_read_b128 v[208:211], v149 offset:55296
	ds_read_b128 v[212:215], v149 offset:56320
	global_load_lds_dwordx4 v[216:217], off
	s_add_i32 m0, s36, 0x2000
	s_add_u32 s34, s34, 0x40080
	v_lshl_add_u64 v[216:217], v[218:219], 0, s[10:11]
	s_addc_u32 s35, s35, 0
	s_add_i32 s36, s84, s47
	global_load_lds_dwordx4 v[216:217], off
	v_lshl_add_u64 v[216:217], s[34:35], 0, v[130:131]
	s_mov_b32 m0, s36
	s_nop 0
	global_load_lds_dwordx4 v[216:217], off
	v_lshl_add_u64 v[216:217], s[34:35], 0, v[134:135]
	s_add_i32 m0, s36, 0x2000
	s_nop 0
	global_load_lds_dwordx4 v[216:217], off
	v_lshl_add_u64 v[216:217], v[220:221], 0, s[10:11]
	s_mov_b32 m0, s65
	s_nop 0
	global_load_lds_dwordx4 v[216:217], off
	v_lshl_add_u64 v[216:217], v[222:223], 0, s[10:11]
	s_mov_b32 m0, s66
	s_nop 0
	global_load_lds_dwordx4 v[216:217], off
	s_waitcnt vmcnt(8)
	s_waitcnt lgkmcnt(0)
	s_barrier
	s_setprio 1
	s_waitcnt lgkmcnt(0)
	v_mfma_f32_16x16x32_bf16 v[60:63], v[150:153], v[182:185], v[60:63]
	v_mfma_f32_16x16x32_bf16 v[56:59], v[158:161], v[182:185], v[56:59]
	v_mfma_f32_16x16x32_bf16 v[52:55], v[150:153], v[190:193], v[52:55]
	v_mfma_f32_16x16x32_bf16 v[48:51], v[158:161], v[190:193], v[48:51]
	v_mfma_f32_16x16x32_bf16 v[36:39], v[150:153], v[198:201], v[36:39]
	v_mfma_f32_16x16x32_bf16 v[32:35], v[158:161], v[198:201], v[32:35]
	v_mfma_f32_16x16x32_bf16 v[20:23], v[150:153], v[208:211], v[20:23]
	v_mfma_f32_16x16x32_bf16 v[16:19], v[158:161], v[208:211], v[16:19]
	v_mfma_f32_16x16x32_bf16 v[60:63], v[154:157], v[186:189], v[60:63]
	v_mfma_f32_16x16x32_bf16 v[56:59], v[162:165], v[186:189], v[56:59]
	v_mfma_f32_16x16x32_bf16 v[52:55], v[154:157], v[194:197], v[52:55]
	v_mfma_f32_16x16x32_bf16 v[48:51], v[162:165], v[194:197], v[48:51]
	v_mfma_f32_16x16x32_bf16 v[36:39], v[154:157], v[202:205], v[36:39]
	v_mfma_f32_16x16x32_bf16 v[32:35], v[162:165], v[202:205], v[32:35]
	v_mfma_f32_16x16x32_bf16 v[20:23], v[154:157], v[212:215], v[20:23]
	v_mfma_f32_16x16x32_bf16 v[16:19], v[162:165], v[212:215], v[16:19]
	s_setprio 0
	s_setprio 1
	v_mfma_f32_16x16x32_bf16 v[44:47], v[166:169], v[182:185], v[44:47]
	v_mfma_f32_16x16x32_bf16 v[40:43], v[174:177], v[182:185], v[40:43]
	v_mfma_f32_16x16x32_bf16 v[28:31], v[166:169], v[190:193], v[28:31]
	v_mfma_f32_16x16x32_bf16 v[24:27], v[174:177], v[190:193], v[24:27]
	v_mfma_f32_16x16x32_bf16 v[12:15], v[166:169], v[198:201], v[12:15]
	v_mfma_f32_16x16x32_bf16 v[8:11], v[174:177], v[198:201], v[8:11]
	v_mfma_f32_16x16x32_bf16 v[4:7], v[166:169], v[208:211], v[4:7]
	v_mfma_f32_16x16x32_bf16 v[0:3], v[174:177], v[208:211], v[0:3]
	v_mfma_f32_16x16x32_bf16 v[44:47], v[170:173], v[186:189], v[44:47]
	v_mfma_f32_16x16x32_bf16 v[40:43], v[178:181], v[186:189], v[40:43]
	v_mfma_f32_16x16x32_bf16 v[28:31], v[170:173], v[194:197], v[28:31]
	v_mfma_f32_16x16x32_bf16 v[24:27], v[178:181], v[194:197], v[24:27]
	v_mfma_f32_16x16x32_bf16 v[12:15], v[170:173], v[202:205], v[12:15]
	v_mfma_f32_16x16x32_bf16 v[8:11], v[178:181], v[202:205], v[8:11]
	v_mfma_f32_16x16x32_bf16 v[4:7], v[170:173], v[212:215], v[4:7]
	v_mfma_f32_16x16x32_bf16 v[0:3], v[178:181], v[212:215], v[0:3]
	s_setprio 0
	s_add_i32 s82, s82, 2
	s_add_u32 s30, s30, 0x100
	s_addc_u32 s31, s31, 0
	s_add_u32 s79, s79, 0x100
	s_addc_u32 s81, s81, 0
	s_cmp_gt_u32 s82, 13
	s_barrier
	s_cbranch_scc0 .LBB0_525
	s_and_b64 vcc, exec, s[12:13]
	s_cbranch_vccz .LBB0_528
	s_barrier

.LBB0_654:
	ds_read_b128 v[146:149], v157
	ds_read_b128 v[150:153], v157 offset:1024
	ds_read_b128 v[162:165], v157 offset:2048
	ds_read_b128 v[166:169], v157 offset:3072
	ds_read_b128 v[170:173], v158
	ds_read_b128 v[174:177], v158 offset:1024
	ds_read_b128 v[178:181], v158 offset:2048
	ds_read_b128 v[182:185], v158 offset:3072
	s_add_u32 s36, s34, 0xfffc0080
	s_addc_u32 s37, s35, -1
	s_cmp_eq_u32 s79, 12
	s_cselect_b32 s41, s5, s37
	s_cselect_b32 s40, s25, s36
	s_cselect_b32 s37, s23, s78
	s_cselect_b32 s36, s76, s77
	v_lshl_add_u64 v[220:221], s[34:35], 0, v[138:139]
	s_add_i32 m0, s31, 0xc000
	ds_read_b128 v[186:189], v159
	ds_read_b128 v[190:193], v159 offset:1024
	ds_read_b128 v[194:197], v159 offset:2048
	ds_read_b128 v[198:201], v159 offset:3072
	ds_read_b128 v[202:205], v159 offset:4096
	ds_read_b128 v[208:211], v159 offset:5120
	ds_read_b128 v[212:215], v159 offset:6144
	ds_read_b128 v[216:219], v159 offset:7168
	global_load_lds_dwordx4 v[220:221], off
	v_lshl_add_u64 v[220:221], s[34:35], 0, v[140:141]
	s_add_i32 m0, s31, 0xe000
	s_nop 0
	global_load_lds_dwordx4 v[220:221], off
	s_waitcnt vmcnt(8)
	s_waitcnt lgkmcnt(0)
	s_barrier
	s_setprio 1
	s_waitcnt lgkmcnt(0)
	v_mfma_f32_16x16x32_bf16 v[124:127], v[146:149], v[186:189], v[124:127]
	v_mfma_f32_16x16x32_bf16 v[120:123], v[162:165], v[186:189], v[120:123]
	v_mfma_f32_16x16x32_bf16 v[108:111], v[146:149], v[194:197], v[108:111]
	v_mfma_f32_16x16x32_bf16 v[104:107], v[162:165], v[194:197], v[104:107]
	v_mfma_f32_16x16x32_bf16 v[92:95], v[146:149], v[202:205], v[92:95]
	v_mfma_f32_16x16x32_bf16 v[88:91], v[162:165], v[202:205], v[88:91]
	v_mfma_f32_16x16x32_bf16 v[76:79], v[146:149], v[212:215], v[76:79]
	v_mfma_f32_16x16x32_bf16 v[72:75], v[162:165], v[212:215], v[72:75]
	v_mfma_f32_16x16x32_bf16 v[124:127], v[150:153], v[190:193], v[124:127]
	v_mfma_f32_16x16x32_bf16 v[120:123], v[166:169], v[190:193], v[120:123]
	v_mfma_f32_16x16x32_bf16 v[108:111], v[150:153], v[198:201], v[108:111]
	v_mfma_f32_16x16x32_bf16 v[104:107], v[166:169], v[198:201], v[104:107]
	v_mfma_f32_16x16x32_bf16 v[92:95], v[150:153], v[208:211], v[92:95]
	v_mfma_f32_16x16x32_bf16 v[88:91], v[166:169], v[208:211], v[88:91]
	v_mfma_f32_16x16x32_bf16 v[76:79], v[150:153], v[216:219], v[76:79]
	v_mfma_f32_16x16x32_bf16 v[72:75], v[166:169], v[216:219], v[72:75]
	s_setprio 0
	s_setprio 1
	v_mfma_f32_16x16x32_bf16 v[116:119], v[170:173], v[186:189], v[116:119]
	v_mfma_f32_16x16x32_bf16 v[112:115], v[178:181], v[186:189], v[112:115]
	v_mfma_f32_16x16x32_bf16 v[100:103], v[170:173], v[194:197], v[100:103]
	v_mfma_f32_16x16x32_bf16 v[96:99], v[178:181], v[194:197], v[96:99]
	v_mfma_f32_16x16x32_bf16 v[84:87], v[170:173], v[202:205], v[84:87]
	v_mfma_f32_16x16x32_bf16 v[80:83], v[178:181], v[202:205], v[80:83]
	v_mfma_f32_16x16x32_bf16 v[68:71], v[170:173], v[212:215], v[68:71]
	v_mfma_f32_16x16x32_bf16 v[64:67], v[178:181], v[212:215], v[64:67]
	v_mfma_f32_16x16x32_bf16 v[116:119], v[174:177], v[190:193], v[116:119]
	v_mfma_f32_16x16x32_bf16 v[112:115], v[182:185], v[190:193], v[112:115]
	v_mfma_f32_16x16x32_bf16 v[100:103], v[174:177], v[198:201], v[100:103]
	v_mfma_f32_16x16x32_bf16 v[96:99], v[182:185], v[198:201], v[96:99]
	v_mfma_f32_16x16x32_bf16 v[84:87], v[174:177], v[208:211], v[84:87]
	v_mfma_f32_16x16x32_bf16 v[80:83], v[182:185], v[208:211], v[80:83]
	v_mfma_f32_16x16x32_bf16 v[68:71], v[174:177], v[216:219], v[68:71]
	v_mfma_f32_16x16x32_bf16 v[64:67], v[182:185], v[216:219], v[64:67]
	s_setprio 0
	s_barrier
	s_add_i32 s81, s70, s46
	v_lshl_add_u64 v[220:221], s[36:37], 0, v[130:131]
	s_mov_b32 m0, s81
	ds_read_b128 v[186:189], v159 offset:16384
	ds_read_b128 v[190:193], v159 offset:17408
	ds_read_b128 v[194:197], v159 offset:18432
	ds_read_b128 v[198:201], v159 offset:19456
	ds_read_b128 v[202:205], v159 offset:20480
	ds_read_b128 v[208:211], v159 offset:21504
	ds_read_b128 v[212:215], v159 offset:22528
	ds_read_b128 v[216:219], v159 offset:23552
	global_load_lds_dwordx4 v[220:221], off
	s_add_i32 m0, s81, 0x2000
	s_add_u32 s82, s36, 0x40000
	v_lshl_add_u64 v[222:223], s[36:37], 0, v[134:135]
	s_addc_u32 s83, s37, 0
	s_add_i32 s81, s71, s46
	global_load_lds_dwordx4 v[222:223], off
	v_lshl_add_u64 v[224:225], s[82:83], 0, v[130:131]
	s_mov_b32 m0, s81
	v_lshl_add_u64 v[226:227], s[40:41], 0, v[132:133]
	global_load_lds_dwordx4 v[224:225], off
	v_lshl_add_u64 v[224:225], s[82:83], 0, v[134:135]
	s_add_i32 m0, s81, 0x2000
	s_nop 0
	global_load_lds_dwordx4 v[224:225], off
	v_lshl_add_u64 v[224:225], s[40:41], 0, v[128:129]
	s_mov_b32 m0, s31
	s_nop 0
	global_load_lds_dwordx4 v[224:225], off
	s_mov_b32 m0, s47
	s_nop 0
	global_load_lds_dwordx4 v[226:227], off
	s_waitcnt vmcnt(8)
	s_waitcnt lgkmcnt(0)
	s_barrier
	s_setprio 1
	s_waitcnt lgkmcnt(0)
	v_mfma_f32_16x16x32_bf16 v[60:63], v[146:149], v[186:189], v[60:63]
	v_mfma_f32_16x16x32_bf16 v[56:59], v[162:165], v[186:189], v[56:59]
	v_mfma_f32_16x16x32_bf16 v[44:47], v[146:149], v[194:197], v[44:47]
	v_mfma_f32_16x16x32_bf16 v[40:43], v[162:165], v[194:197], v[40:43]
	v_mfma_f32_16x16x32_bf16 v[28:31], v[146:149], v[202:205], v[28:31]
	v_mfma_f32_16x16x32_bf16 v[24:27], v[162:165], v[202:205], v[24:27]
	v_mfma_f32_16x16x32_bf16 v[12:15], v[146:149], v[212:215], v[12:15]
	v_mfma_f32_16x16x32_bf16 v[8:11], v[162:165], v[212:215], v[8:11]
	v_mfma_f32_16x16x32_bf16 v[60:63], v[150:153], v[190:193], v[60:63]
	v_mfma_f32_16x16x32_bf16 v[56:59], v[166:169], v[190:193], v[56:59]
	v_mfma_f32_16x16x32_bf16 v[44:47], v[150:153], v[198:201], v[44:47]
	v_mfma_f32_16x16x32_bf16 v[40:43], v[166:169], v[198:201], v[40:43]
	v_mfma_f32_16x16x32_bf16 v[28:31], v[150:153], v[208:211], v[28:31]
	v_mfma_f32_16x16x32_bf16 v[24:27], v[166:169], v[208:211], v[24:27]
	v_mfma_f32_16x16x32_bf16 v[12:15], v[150:153], v[216:219], v[12:15]
	v_mfma_f32_16x16x32_bf16 v[8:11], v[166:169], v[216:219], v[8:11]
	s_setprio 0
	s_setprio 1
	v_mfma_f32_16x16x32_bf16 v[52:55], v[170:173], v[186:189], v[52:55]
	v_mfma_f32_16x16x32_bf16 v[48:51], v[178:181], v[186:189], v[48:51]
	v_mfma_f32_16x16x32_bf16 v[36:39], v[170:173], v[194:197], v[36:39]
	v_mfma_f32_16x16x32_bf16 v[32:35], v[178:181], v[194:197], v[32:35]
	v_mfma_f32_16x16x32_bf16 v[20:23], v[170:173], v[202:205], v[20:23]
	v_mfma_f32_16x16x32_bf16 v[16:19], v[178:181], v[202:205], v[16:19]
	v_mfma_f32_16x16x32_bf16 v[4:7], v[170:173], v[212:215], v[4:7]
	v_mfma_f32_16x16x32_bf16 v[0:3], v[178:181], v[212:215], v[0:3]
	v_mfma_f32_16x16x32_bf16 v[52:55], v[174:177], v[190:193], v[52:55]
	v_mfma_f32_16x16x32_bf16 v[48:51], v[182:185], v[190:193], v[48:51]
	v_mfma_f32_16x16x32_bf16 v[36:39], v[174:177], v[198:201], v[36:39]
	v_mfma_f32_16x16x32_bf16 v[32:35], v[182:185], v[198:201], v[32:35]
	v_mfma_f32_16x16x32_bf16 v[20:23], v[174:177], v[208:211], v[20:23]
	v_mfma_f32_16x16x32_bf16 v[16:19], v[182:185], v[208:211], v[16:19]
	v_mfma_f32_16x16x32_bf16 v[4:7], v[174:177], v[216:219], v[4:7]
	v_mfma_f32_16x16x32_bf16 v[0:3], v[182:185], v[216:219], v[0:3]
	s_setprio 0
	s_barrier
	s_add_i32 s81, 0, 0x18000
	v_add_u32_e32 v136, s81, v155
	s_add_i32 s82, 0, 0x1c000
	ds_read_b128 v[146:149], v136
	ds_read_b128 v[150:153], v136 offset:1024
	ds_read_b128 v[162:165], v136 offset:2048
	ds_read_b128 v[166:169], v136 offset:3072
	v_add_u32_e32 v136, s82, v155
	ds_read_b128 v[170:173], v136
	ds_read_b128 v[174:177], v136 offset:1024
	ds_read_b128 v[178:181], v136 offset:2048
	ds_read_b128 v[182:185], v136 offset:3072
	s_add_u32 s40, s40, 0x40000
	s_addc_u32 s41, s41, 0
	s_mov_b32 m0, s48
	v_lshl_add_u64 v[228:229], s[40:41], 0, v[128:129]
	ds_read_b128 v[186:189], v159 offset:32768
	ds_read_b128 v[190:193], v159 offset:33792
	ds_read_b128 v[194:197], v159 offset:34816
	ds_read_b128 v[198:201], v159 offset:35840
	ds_read_b128 v[202:205], v159 offset:36864
	ds_read_b128 v[208:211], v159 offset:37888
	ds_read_b128 v[212:215], v159 offset:38912
	ds_read_b128 v[216:219], v159 offset:39936
	global_load_lds_dwordx4 v[228:229], off
	v_lshl_add_u64 v[228:229], s[40:41], 0, v[132:133]
	s_mov_b32 m0, s49
	s_nop 0
	global_load_lds_dwordx4 v[228:229], off
	s_waitcnt vmcnt(8)
	s_waitcnt lgkmcnt(0)
	s_barrier
	s_setprio 1
	s_waitcnt lgkmcnt(0)
	v_mfma_f32_16x16x32_bf16 v[124:127], v[146:149], v[186:189], v[124:127]
	v_mfma_f32_16x16x32_bf16 v[120:123], v[162:165], v[186:189], v[120:123]
	v_mfma_f32_16x16x32_bf16 v[108:111], v[146:149], v[194:197], v[108:111]
	v_mfma_f32_16x16x32_bf16 v[104:107], v[162:165], v[194:197], v[104:107]
	v_mfma_f32_16x16x32_bf16 v[92:95], v[146:149], v[202:205], v[92:95]
	v_mfma_f32_16x16x32_bf16 v[88:91], v[162:165], v[202:205], v[88:91]
	v_mfma_f32_16x16x32_bf16 v[76:79], v[146:149], v[212:215], v[76:79]
	v_mfma_f32_16x16x32_bf16 v[72:75], v[162:165], v[212:215], v[72:75]
	v_mfma_f32_16x16x32_bf16 v[124:127], v[150:153], v[190:193], v[124:127]
	v_mfma_f32_16x16x32_bf16 v[120:123], v[166:169], v[190:193], v[120:123]
	v_mfma_f32_16x16x32_bf16 v[108:111], v[150:153], v[198:201], v[108:111]
	v_mfma_f32_16x16x32_bf16 v[104:107], v[166:169], v[198:201], v[104:107]
	v_mfma_f32_16x16x32_bf16 v[92:95], v[150:153], v[208:211], v[92:95]
	v_mfma_f32_16x16x32_bf16 v[88:91], v[166:169], v[208:211], v[88:91]
	v_mfma_f32_16x16x32_bf16 v[76:79], v[150:153], v[216:219], v[76:79]
	v_mfma_f32_16x16x32_bf16 v[72:75], v[166:169], v[216:219], v[72:75]
	s_setprio 0
	s_setprio 1
	v_mfma_f32_16x16x32_bf16 v[116:119], v[170:173], v[186:189], v[116:119]
	v_mfma_f32_16x16x32_bf16 v[112:115], v[178:181], v[186:189], v[112:115]
	v_mfma_f32_16x16x32_bf16 v[100:103], v[170:173], v[194:197], v[100:103]
	v_mfma_f32_16x16x32_bf16 v[96:99], v[178:181], v[194:197], v[96:99]
	v_mfma_f32_16x16x32_bf16 v[84:87], v[170:173], v[202:205], v[84:87]
	v_mfma_f32_16x16x32_bf16 v[80:83], v[178:181], v[202:205], v[80:83]
	v_mfma_f32_16x16x32_bf16 v[68:71], v[170:173], v[212:215], v[68:71]
	v_mfma_f32_16x16x32_bf16 v[64:67], v[178:181], v[212:215], v[64:67]
	v_mfma_f32_16x16x32_bf16 v[116:119], v[174:177], v[190:193], v[116:119]
	v_mfma_f32_16x16x32_bf16 v[112:115], v[182:185], v[190:193], v[112:115]
	v_mfma_f32_16x16x32_bf16 v[100:103], v[174:177], v[198:201], v[100:103]
	v_mfma_f32_16x16x32_bf16 v[96:99], v[182:185], v[198:201], v[96:99]
	v_mfma_f32_16x16x32_bf16 v[84:87], v[174:177], v[208:211], v[84:87]
	v_mfma_f32_16x16x32_bf16 v[80:83], v[182:185], v[208:211], v[80:83]
	v_mfma_f32_16x16x32_bf16 v[68:71], v[174:177], v[216:219], v[68:71]
	v_mfma_f32_16x16x32_bf16 v[64:67], v[182:185], v[216:219], v[64:67]
	s_setprio 0
	s_barrier
	s_add_i32 s40, s81, s46
	v_lshl_add_u64 v[220:221], v[220:221], 0, s[12:13]
	s_mov_b32 m0, s40
	ds_read_b128 v[186:189], v159 offset:49152
	ds_read_b128 v[190:193], v159 offset:50176
	ds_read_b128 v[194:197], v159 offset:51200
	ds_read_b128 v[198:201], v159 offset:52224
	ds_read_b128 v[202:205], v159 offset:53248
	ds_read_b128 v[208:211], v159 offset:54272
	ds_read_b128 v[212:215], v159 offset:55296
	ds_read_b128 v[216:219], v159 offset:56320
	global_load_lds_dwordx4 v[220:221], off
	s_add_i32 m0, s40, 0x2000
	s_add_u32 s36, s36, 0x40080
	v_lshl_add_u64 v[220:221], v[222:223], 0, s[12:13]
	s_addc_u32 s37, s37, 0
	s_add_i32 s40, s82, s46
	global_load_lds_dwordx4 v[220:221], off
	v_lshl_add_u64 v[220:221], s[36:37], 0, v[130:131]
	s_mov_b32 m0, s40
	s_nop 0
	global_load_lds_dwordx4 v[220:221], off
	v_lshl_add_u64 v[220:221], s[36:37], 0, v[134:135]
	s_add_i32 m0, s40, 0x2000
	s_nop 0
	global_load_lds_dwordx4 v[220:221], off
	v_lshl_add_u64 v[220:221], v[224:225], 0, s[12:13]
	s_mov_b32 m0, s65
	s_nop 0
	global_load_lds_dwordx4 v[220:221], off
	v_lshl_add_u64 v[220:221], v[226:227], 0, s[12:13]
	s_mov_b32 m0, s66
	s_nop 0
	global_load_lds_dwordx4 v[220:221], off
	s_waitcnt vmcnt(8)
	s_waitcnt lgkmcnt(0)
	s_barrier
	s_setprio 1
	s_waitcnt lgkmcnt(0)
	v_mfma_f32_16x16x32_bf16 v[60:63], v[146:149], v[186:189], v[60:63]
	v_mfma_f32_16x16x32_bf16 v[56:59], v[162:165], v[186:189], v[56:59]
	v_mfma_f32_16x16x32_bf16 v[44:47], v[146:149], v[194:197], v[44:47]
	v_mfma_f32_16x16x32_bf16 v[40:43], v[162:165], v[194:197], v[40:43]
	v_mfma_f32_16x16x32_bf16 v[28:31], v[146:149], v[202:205], v[28:31]
	v_mfma_f32_16x16x32_bf16 v[24:27], v[162:165], v[202:205], v[24:27]
	v_mfma_f32_16x16x32_bf16 v[12:15], v[146:149], v[212:215], v[12:15]
	v_mfma_f32_16x16x32_bf16 v[8:11], v[162:165], v[212:215], v[8:11]
	v_mfma_f32_16x16x32_bf16 v[60:63], v[150:153], v[190:193], v[60:63]
	v_mfma_f32_16x16x32_bf16 v[56:59], v[166:169], v[190:193], v[56:59]
	v_mfma_f32_16x16x32_bf16 v[44:47], v[150:153], v[198:201], v[44:47]
	v_mfma_f32_16x16x32_bf16 v[40:43], v[166:169], v[198:201], v[40:43]
	v_mfma_f32_16x16x32_bf16 v[28:31], v[150:153], v[208:211], v[28:31]
	v_mfma_f32_16x16x32_bf16 v[24:27], v[166:169], v[208:211], v[24:27]
	v_mfma_f32_16x16x32_bf16 v[12:15], v[150:153], v[216:219], v[12:15]
	v_mfma_f32_16x16x32_bf16 v[8:11], v[166:169], v[216:219], v[8:11]
	s_setprio 0
	s_setprio 1
	v_mfma_f32_16x16x32_bf16 v[52:55], v[170:173], v[186:189], v[52:55]
	v_mfma_f32_16x16x32_bf16 v[48:51], v[178:181], v[186:189], v[48:51]
	v_mfma_f32_16x16x32_bf16 v[36:39], v[170:173], v[194:197], v[36:39]
	v_mfma_f32_16x16x32_bf16 v[32:35], v[178:181], v[194:197], v[32:35]
	v_mfma_f32_16x16x32_bf16 v[20:23], v[170:173], v[202:205], v[20:23]
	v_mfma_f32_16x16x32_bf16 v[16:19], v[178:181], v[202:205], v[16:19]
	v_mfma_f32_16x16x32_bf16 v[4:7], v[170:173], v[212:215], v[4:7]
	v_mfma_f32_16x16x32_bf16 v[0:3], v[178:181], v[212:215], v[0:3]
	v_mfma_f32_16x16x32_bf16 v[52:55], v[174:177], v[190:193], v[52:55]
	v_mfma_f32_16x16x32_bf16 v[48:51], v[182:185], v[190:193], v[48:51]
	v_mfma_f32_16x16x32_bf16 v[36:39], v[174:177], v[198:201], v[36:39]
	v_mfma_f32_16x16x32_bf16 v[32:35], v[182:185], v[198:201], v[32:35]
	v_mfma_f32_16x16x32_bf16 v[20:23], v[174:177], v[208:211], v[20:23]
	v_mfma_f32_16x16x32_bf16 v[16:19], v[182:185], v[208:211], v[16:19]
	v_mfma_f32_16x16x32_bf16 v[4:7], v[174:177], v[216:219], v[4:7]
	v_mfma_f32_16x16x32_bf16 v[0:3], v[182:185], v[216:219], v[0:3]
	s_setprio 0
	s_add_i32 s79, s79, 2
	s_add_u32 s34, s34, 0x100
	s_addc_u32 s35, s35, 0
	s_add_u32 s77, s77, 0x100
	s_addc_u32 s78, s78, 0
	s_cmp_gt_u32 s79, 13
	s_barrier
	s_cbranch_scc0 .LBB0_654
	s_and_b64 vcc, exec, s[14:15]
	s_cbranch_vccz .LBB0_657
	s_barrier

.LBB0_867:
	ds_read_b128 v[150:153], v147
	ds_read_b128 v[154:157], v147 offset:1024
	ds_read_b128 v[158:161], v147 offset:2048
	ds_read_b128 v[162:165], v147 offset:3072
	ds_read_b128 v[166:169], v148
	ds_read_b128 v[170:173], v148 offset:1024
	ds_read_b128 v[174:177], v148 offset:2048
	ds_read_b128 v[178:181], v148 offset:3072
	s_add_u32 s30, s28, 0xfffc0080
	s_addc_u32 s31, s29, -1
	s_cmp_eq_u32 s73, 12
	s_cselect_b32 s35, s23, s31
	s_cselect_b32 s34, s67, s30
	s_cselect_b32 s31, s21, s72
	s_cselect_b32 s30, s70, s71
	v_lshl_add_u64 v[216:217], s[28:29], 0, v[136:137]
	s_add_i32 m0, s19, 0xc000
	ds_read_b128 v[182:185], v149
	ds_read_b128 v[186:189], v149 offset:1024
	ds_read_b128 v[190:193], v149 offset:2048
	ds_read_b128 v[194:197], v149 offset:3072
	ds_read_b128 v[198:201], v149 offset:4096
	ds_read_b128 v[202:205], v149 offset:5120
	ds_read_b128 v[208:211], v149 offset:6144
	ds_read_b128 v[212:215], v149 offset:7168
	global_load_lds_dwordx4 v[216:217], off
	v_lshl_add_u64 v[216:217], s[28:29], 0, v[138:139]
	s_add_i32 m0, s19, 0xe000
	s_nop 0
	global_load_lds_dwordx4 v[216:217], off
	s_waitcnt vmcnt(8)
	s_waitcnt lgkmcnt(0)
	s_barrier
	s_setprio 1
	s_waitcnt lgkmcnt(0)
	v_mfma_f32_16x16x32_bf16 v[124:127], v[150:153], v[182:185], v[124:127]
	v_mfma_f32_16x16x32_bf16 v[120:123], v[158:161], v[182:185], v[120:123]
	v_mfma_f32_16x16x32_bf16 v[116:119], v[150:153], v[190:193], v[116:119]
	v_mfma_f32_16x16x32_bf16 v[112:115], v[158:161], v[190:193], v[112:115]
	v_mfma_f32_16x16x32_bf16 v[100:103], v[150:153], v[198:201], v[100:103]
	v_mfma_f32_16x16x32_bf16 v[96:99], v[158:161], v[198:201], v[96:99]
	v_mfma_f32_16x16x32_bf16 v[84:87], v[150:153], v[208:211], v[84:87]
	v_mfma_f32_16x16x32_bf16 v[80:83], v[158:161], v[208:211], v[80:83]
	v_mfma_f32_16x16x32_bf16 v[124:127], v[154:157], v[186:189], v[124:127]
	v_mfma_f32_16x16x32_bf16 v[120:123], v[162:165], v[186:189], v[120:123]
	v_mfma_f32_16x16x32_bf16 v[116:119], v[154:157], v[194:197], v[116:119]
	v_mfma_f32_16x16x32_bf16 v[112:115], v[162:165], v[194:197], v[112:115]
	v_mfma_f32_16x16x32_bf16 v[100:103], v[154:157], v[202:205], v[100:103]
	v_mfma_f32_16x16x32_bf16 v[96:99], v[162:165], v[202:205], v[96:99]
	v_mfma_f32_16x16x32_bf16 v[84:87], v[154:157], v[212:215], v[84:87]
	v_mfma_f32_16x16x32_bf16 v[80:83], v[162:165], v[212:215], v[80:83]
	s_setprio 0
	s_setprio 1
	v_mfma_f32_16x16x32_bf16 v[108:111], v[166:169], v[182:185], v[108:111]
	v_mfma_f32_16x16x32_bf16 v[104:107], v[174:177], v[182:185], v[104:107]
	v_mfma_f32_16x16x32_bf16 v[92:95], v[166:169], v[190:193], v[92:95]
	v_mfma_f32_16x16x32_bf16 v[88:91], v[174:177], v[190:193], v[88:91]
	v_mfma_f32_16x16x32_bf16 v[76:79], v[166:169], v[198:201], v[76:79]
	v_mfma_f32_16x16x32_bf16 v[72:75], v[174:177], v[198:201], v[72:75]
	v_mfma_f32_16x16x32_bf16 v[68:71], v[166:169], v[208:211], v[68:71]
	v_mfma_f32_16x16x32_bf16 v[64:67], v[174:177], v[208:211], v[64:67]
	v_mfma_f32_16x16x32_bf16 v[108:111], v[170:173], v[186:189], v[108:111]
	v_mfma_f32_16x16x32_bf16 v[104:107], v[178:181], v[186:189], v[104:107]
	v_mfma_f32_16x16x32_bf16 v[92:95], v[170:173], v[194:197], v[92:95]
	v_mfma_f32_16x16x32_bf16 v[88:91], v[178:181], v[194:197], v[88:91]
	v_mfma_f32_16x16x32_bf16 v[76:79], v[170:173], v[202:205], v[76:79]
	v_mfma_f32_16x16x32_bf16 v[72:75], v[178:181], v[202:205], v[72:75]
	v_mfma_f32_16x16x32_bf16 v[68:71], v[170:173], v[212:215], v[68:71]
	v_mfma_f32_16x16x32_bf16 v[64:67], v[178:181], v[212:215], v[64:67]
	s_setprio 0
	s_barrier
	s_add_i32 s74, s51, s39
	v_lshl_add_u64 v[216:217], s[30:31], 0, v[130:131]
	s_mov_b32 m0, s74
	ds_read_b128 v[182:185], v149 offset:16384
	ds_read_b128 v[186:189], v149 offset:17408
	ds_read_b128 v[190:193], v149 offset:18432
	ds_read_b128 v[194:197], v149 offset:19456
	ds_read_b128 v[198:201], v149 offset:20480
	ds_read_b128 v[202:205], v149 offset:21504
	ds_read_b128 v[208:211], v149 offset:22528
	ds_read_b128 v[212:215], v149 offset:23552
	global_load_lds_dwordx4 v[216:217], off
	s_add_i32 m0, s74, 0x2000
	s_add_u32 s74, s30, 0x40000
	v_lshl_add_u64 v[218:219], s[30:31], 0, v[134:135]
	s_addc_u32 s75, s31, 0
	s_add_i32 s76, s52, s39
	global_load_lds_dwordx4 v[218:219], off
	v_lshl_add_u64 v[220:221], s[74:75], 0, v[130:131]
	s_mov_b32 m0, s76
	v_lshl_add_u64 v[222:223], s[34:35], 0, v[132:133]
	global_load_lds_dwordx4 v[220:221], off
	v_lshl_add_u64 v[220:221], s[74:75], 0, v[134:135]
	s_add_i32 m0, s76, 0x2000
	s_nop 0
	global_load_lds_dwordx4 v[220:221], off
	v_lshl_add_u64 v[220:221], s[34:35], 0, v[128:129]
	s_mov_b32 m0, s19
	s_nop 0
	global_load_lds_dwordx4 v[220:221], off
	s_mov_b32 m0, s40
	s_nop 0
	global_load_lds_dwordx4 v[222:223], off
	s_waitcnt vmcnt(8)
	s_waitcnt lgkmcnt(0)
	s_barrier
	s_setprio 1
	s_waitcnt lgkmcnt(0)
	v_mfma_f32_16x16x32_bf16 v[60:63], v[150:153], v[182:185], v[60:63]
	v_mfma_f32_16x16x32_bf16 v[56:59], v[158:161], v[182:185], v[56:59]
	v_mfma_f32_16x16x32_bf16 v[52:55], v[150:153], v[190:193], v[52:55]
	v_mfma_f32_16x16x32_bf16 v[48:51], v[158:161], v[190:193], v[48:51]
	v_mfma_f32_16x16x32_bf16 v[36:39], v[150:153], v[198:201], v[36:39]
	v_mfma_f32_16x16x32_bf16 v[32:35], v[158:161], v[198:201], v[32:35]
	v_mfma_f32_16x16x32_bf16 v[20:23], v[150:153], v[208:211], v[20:23]
	v_mfma_f32_16x16x32_bf16 v[16:19], v[158:161], v[208:211], v[16:19]
	v_mfma_f32_16x16x32_bf16 v[60:63], v[154:157], v[186:189], v[60:63]
	v_mfma_f32_16x16x32_bf16 v[56:59], v[162:165], v[186:189], v[56:59]
	v_mfma_f32_16x16x32_bf16 v[52:55], v[154:157], v[194:197], v[52:55]
	v_mfma_f32_16x16x32_bf16 v[48:51], v[162:165], v[194:197], v[48:51]
	v_mfma_f32_16x16x32_bf16 v[36:39], v[154:157], v[202:205], v[36:39]
	v_mfma_f32_16x16x32_bf16 v[32:35], v[162:165], v[202:205], v[32:35]
	v_mfma_f32_16x16x32_bf16 v[20:23], v[154:157], v[212:215], v[20:23]
	v_mfma_f32_16x16x32_bf16 v[16:19], v[162:165], v[212:215], v[16:19]
	s_setprio 0
	s_setprio 1
	v_mfma_f32_16x16x32_bf16 v[44:47], v[166:169], v[182:185], v[44:47]
	v_mfma_f32_16x16x32_bf16 v[40:43], v[174:177], v[182:185], v[40:43]
	v_mfma_f32_16x16x32_bf16 v[28:31], v[166:169], v[190:193], v[28:31]
	v_mfma_f32_16x16x32_bf16 v[24:27], v[174:177], v[190:193], v[24:27]
	v_mfma_f32_16x16x32_bf16 v[12:15], v[166:169], v[198:201], v[12:15]
	v_mfma_f32_16x16x32_bf16 v[8:11], v[174:177], v[198:201], v[8:11]
	v_mfma_f32_16x16x32_bf16 v[4:7], v[166:169], v[208:211], v[4:7]
	v_mfma_f32_16x16x32_bf16 v[0:3], v[174:177], v[208:211], v[0:3]
	v_mfma_f32_16x16x32_bf16 v[44:47], v[170:173], v[186:189], v[44:47]
	v_mfma_f32_16x16x32_bf16 v[40:43], v[178:181], v[186:189], v[40:43]
	v_mfma_f32_16x16x32_bf16 v[28:31], v[170:173], v[194:197], v[28:31]
	v_mfma_f32_16x16x32_bf16 v[24:27], v[178:181], v[194:197], v[24:27]
	v_mfma_f32_16x16x32_bf16 v[12:15], v[170:173], v[202:205], v[12:15]
	v_mfma_f32_16x16x32_bf16 v[8:11], v[178:181], v[202:205], v[8:11]
	v_mfma_f32_16x16x32_bf16 v[4:7], v[170:173], v[212:215], v[4:7]
	v_mfma_f32_16x16x32_bf16 v[0:3], v[178:181], v[212:215], v[0:3]
	s_setprio 0
	s_barrier
	s_add_i32 s74, 0, 0x18000
	s_add_i32 s75, 0, 0x1c000
	v_add_u32_e32 v162, s74, v145
	v_add_u32_e32 v178, s75, v145
	ds_read_b128 v[150:153], v162
	ds_read_b128 v[154:157], v162 offset:1024
	ds_read_b128 v[158:161], v162 offset:2048
	ds_read_b128 v[162:165], v162 offset:3072
	ds_read_b128 v[166:169], v178
	ds_read_b128 v[170:173], v178 offset:1024
	ds_read_b128 v[174:177], v178 offset:2048
	ds_read_b128 v[178:181], v178 offset:3072
	s_add_u32 s34, s34, 0x40000
	s_addc_u32 s35, s35, 0
	s_mov_b32 m0, s41
	v_lshl_add_u64 v[224:225], s[34:35], 0, v[128:129]
	ds_read_b128 v[182:185], v149 offset:32768
	ds_read_b128 v[186:189], v149 offset:33792
	ds_read_b128 v[190:193], v149 offset:34816
	ds_read_b128 v[194:197], v149 offset:35840
	ds_read_b128 v[198:201], v149 offset:36864
	ds_read_b128 v[202:205], v149 offset:37888
	ds_read_b128 v[208:211], v149 offset:38912
	ds_read_b128 v[212:215], v149 offset:39936
	global_load_lds_dwordx4 v[224:225], off
	v_lshl_add_u64 v[224:225], s[34:35], 0, v[132:133]
	s_mov_b32 m0, s46
	s_nop 0
	global_load_lds_dwordx4 v[224:225], off
	s_waitcnt vmcnt(8)
	s_waitcnt lgkmcnt(0)
	s_barrier
	s_setprio 1
	s_waitcnt lgkmcnt(0)
	v_mfma_f32_16x16x32_bf16 v[124:127], v[150:153], v[182:185], v[124:127]
	v_mfma_f32_16x16x32_bf16 v[120:123], v[158:161], v[182:185], v[120:123]
	v_mfma_f32_16x16x32_bf16 v[116:119], v[150:153], v[190:193], v[116:119]
	v_mfma_f32_16x16x32_bf16 v[112:115], v[158:161], v[190:193], v[112:115]
	v_mfma_f32_16x16x32_bf16 v[100:103], v[150:153], v[198:201], v[100:103]
	v_mfma_f32_16x16x32_bf16 v[96:99], v[158:161], v[198:201], v[96:99]
	v_mfma_f32_16x16x32_bf16 v[84:87], v[150:153], v[208:211], v[84:87]
	v_mfma_f32_16x16x32_bf16 v[80:83], v[158:161], v[208:211], v[80:83]
	v_mfma_f32_16x16x32_bf16 v[124:127], v[154:157], v[186:189], v[124:127]
	v_mfma_f32_16x16x32_bf16 v[120:123], v[162:165], v[186:189], v[120:123]
	v_mfma_f32_16x16x32_bf16 v[116:119], v[154:157], v[194:197], v[116:119]
	v_mfma_f32_16x16x32_bf16 v[112:115], v[162:165], v[194:197], v[112:115]
	v_mfma_f32_16x16x32_bf16 v[100:103], v[154:157], v[202:205], v[100:103]
	v_mfma_f32_16x16x32_bf16 v[96:99], v[162:165], v[202:205], v[96:99]
	v_mfma_f32_16x16x32_bf16 v[84:87], v[154:157], v[212:215], v[84:87]
	v_mfma_f32_16x16x32_bf16 v[80:83], v[162:165], v[212:215], v[80:83]
	s_setprio 0
	s_setprio 1
	v_mfma_f32_16x16x32_bf16 v[108:111], v[166:169], v[182:185], v[108:111]
	v_mfma_f32_16x16x32_bf16 v[104:107], v[174:177], v[182:185], v[104:107]
	v_mfma_f32_16x16x32_bf16 v[92:95], v[166:169], v[190:193], v[92:95]
	v_mfma_f32_16x16x32_bf16 v[88:91], v[174:177], v[190:193], v[88:91]
	v_mfma_f32_16x16x32_bf16 v[76:79], v[166:169], v[198:201], v[76:79]
	v_mfma_f32_16x16x32_bf16 v[72:75], v[174:177], v[198:201], v[72:75]
	v_mfma_f32_16x16x32_bf16 v[68:71], v[166:169], v[208:211], v[68:71]
	v_mfma_f32_16x16x32_bf16 v[64:67], v[174:177], v[208:211], v[64:67]
	v_mfma_f32_16x16x32_bf16 v[108:111], v[170:173], v[186:189], v[108:111]
	v_mfma_f32_16x16x32_bf16 v[104:107], v[178:181], v[186:189], v[104:107]
	v_mfma_f32_16x16x32_bf16 v[92:95], v[170:173], v[194:197], v[92:95]
	v_mfma_f32_16x16x32_bf16 v[88:91], v[178:181], v[194:197], v[88:91]
	v_mfma_f32_16x16x32_bf16 v[76:79], v[170:173], v[202:205], v[76:79]
	v_mfma_f32_16x16x32_bf16 v[72:75], v[178:181], v[202:205], v[72:75]
	v_mfma_f32_16x16x32_bf16 v[68:71], v[170:173], v[212:215], v[68:71]
	v_mfma_f32_16x16x32_bf16 v[64:67], v[178:181], v[212:215], v[64:67]
	s_setprio 0
	s_barrier
	s_add_i32 s34, s74, s39
	v_lshl_add_u64 v[216:217], v[216:217], 0, s[8:9]
	s_mov_b32 m0, s34
	ds_read_b128 v[182:185], v149 offset:49152
	ds_read_b128 v[186:189], v149 offset:50176
	ds_read_b128 v[190:193], v149 offset:51200
	ds_read_b128 v[194:197], v149 offset:52224
	ds_read_b128 v[198:201], v149 offset:53248
	ds_read_b128 v[202:205], v149 offset:54272
	ds_read_b128 v[208:211], v149 offset:55296
	ds_read_b128 v[212:215], v149 offset:56320
	global_load_lds_dwordx4 v[216:217], off
	s_add_i32 m0, s34, 0x2000
	s_add_u32 s30, s30, 0x40080
	v_lshl_add_u64 v[216:217], v[218:219], 0, s[8:9]
	s_addc_u32 s31, s31, 0
	s_add_i32 s34, s75, s39
	global_load_lds_dwordx4 v[216:217], off
	v_lshl_add_u64 v[216:217], s[30:31], 0, v[130:131]
	s_mov_b32 m0, s34
	s_nop 0
	global_load_lds_dwordx4 v[216:217], off
	v_lshl_add_u64 v[216:217], s[30:31], 0, v[134:135]
	s_add_i32 m0, s34, 0x2000
	s_nop 0
	global_load_lds_dwordx4 v[216:217], off
	v_lshl_add_u64 v[216:217], v[220:221], 0, s[8:9]
	s_mov_b32 m0, s48
	s_nop 0
	global_load_lds_dwordx4 v[216:217], off
	v_lshl_add_u64 v[216:217], v[222:223], 0, s[8:9]
	s_mov_b32 m0, s49
	s_nop 0
	global_load_lds_dwordx4 v[216:217], off
	s_waitcnt vmcnt(8)
	s_waitcnt lgkmcnt(0)
	s_barrier
	s_setprio 1
	s_waitcnt lgkmcnt(0)
	v_mfma_f32_16x16x32_bf16 v[60:63], v[150:153], v[182:185], v[60:63]
	v_mfma_f32_16x16x32_bf16 v[56:59], v[158:161], v[182:185], v[56:59]
	v_mfma_f32_16x16x32_bf16 v[52:55], v[150:153], v[190:193], v[52:55]
	v_mfma_f32_16x16x32_bf16 v[48:51], v[158:161], v[190:193], v[48:51]
	v_mfma_f32_16x16x32_bf16 v[36:39], v[150:153], v[198:201], v[36:39]
	v_mfma_f32_16x16x32_bf16 v[32:35], v[158:161], v[198:201], v[32:35]
	v_mfma_f32_16x16x32_bf16 v[20:23], v[150:153], v[208:211], v[20:23]
	v_mfma_f32_16x16x32_bf16 v[16:19], v[158:161], v[208:211], v[16:19]
	v_mfma_f32_16x16x32_bf16 v[60:63], v[154:157], v[186:189], v[60:63]
	v_mfma_f32_16x16x32_bf16 v[56:59], v[162:165], v[186:189], v[56:59]
	v_mfma_f32_16x16x32_bf16 v[52:55], v[154:157], v[194:197], v[52:55]
	v_mfma_f32_16x16x32_bf16 v[48:51], v[162:165], v[194:197], v[48:51]
	v_mfma_f32_16x16x32_bf16 v[36:39], v[154:157], v[202:205], v[36:39]
	v_mfma_f32_16x16x32_bf16 v[32:35], v[162:165], v[202:205], v[32:35]
	v_mfma_f32_16x16x32_bf16 v[20:23], v[154:157], v[212:215], v[20:23]
	v_mfma_f32_16x16x32_bf16 v[16:19], v[162:165], v[212:215], v[16:19]
	s_setprio 0
	s_setprio 1
	v_mfma_f32_16x16x32_bf16 v[44:47], v[166:169], v[182:185], v[44:47]
	v_mfma_f32_16x16x32_bf16 v[40:43], v[174:177], v[182:185], v[40:43]
	v_mfma_f32_16x16x32_bf16 v[28:31], v[166:169], v[190:193], v[28:31]
	v_mfma_f32_16x16x32_bf16 v[24:27], v[174:177], v[190:193], v[24:27]
	v_mfma_f32_16x16x32_bf16 v[12:15], v[166:169], v[198:201], v[12:15]
	v_mfma_f32_16x16x32_bf16 v[8:11], v[174:177], v[198:201], v[8:11]
	v_mfma_f32_16x16x32_bf16 v[4:7], v[166:169], v[208:211], v[4:7]
	v_mfma_f32_16x16x32_bf16 v[0:3], v[174:177], v[208:211], v[0:3]
	v_mfma_f32_16x16x32_bf16 v[44:47], v[170:173], v[186:189], v[44:47]
	v_mfma_f32_16x16x32_bf16 v[40:43], v[178:181], v[186:189], v[40:43]
	v_mfma_f32_16x16x32_bf16 v[28:31], v[170:173], v[194:197], v[28:31]
	v_mfma_f32_16x16x32_bf16 v[24:27], v[178:181], v[194:197], v[24:27]
	v_mfma_f32_16x16x32_bf16 v[12:15], v[170:173], v[202:205], v[12:15]
	v_mfma_f32_16x16x32_bf16 v[8:11], v[178:181], v[202:205], v[8:11]
	v_mfma_f32_16x16x32_bf16 v[4:7], v[170:173], v[212:215], v[4:7]
	v_mfma_f32_16x16x32_bf16 v[0:3], v[178:181], v[212:215], v[0:3]
	s_setprio 0
	s_add_i32 s73, s73, 2
	s_add_u32 s28, s28, 0x100
	s_addc_u32 s29, s29, 0
	s_add_u32 s71, s71, 0x100
	s_addc_u32 s72, s72, 0
	s_cmp_gt_u32 s73, 13
	s_barrier
	s_cbranch_scc0 .LBB0_867
	s_and_b64 vcc, exec, s[10:11]
	s_cbranch_vccz .LBB0_870
	s_barrier
